# seam 0: the eight per-XCC census re-check loads issued together instead of one round trip each
# baseline (speedup 1.0000x reference)
.LBB0_95:
	s_or_b64 exec, exec, s[4:5]
	s_waitcnt lgkmcnt(0)
	s_barrier
	s_mov_b64 s[4:5], exec
	v_readlane_b32 s6, v255, 1
	v_readlane_b32 s7, v255, 2
	s_and_b64 s[6:7], s[4:5], s[6:7]
	s_mov_b64 exec, s[6:7]
	s_cbranch_execz .LBB0_107
	s_and_b32 s3, s34, 7
	s_cmp_eq_u32 s3, 0
	s_cselect_b64 s[6:7], -1, 0
	s_cmp_lt_u32 s33, 8
	s_cselect_b64 s[8:9], -1, 0
	s_and_b64 s[6:7], s[6:7], s[8:9]
	s_andn2_b64 vcc, exec, s[6:7]
	v_mov_b32_e32 v0, s80
	s_cbranch_vccnz .LBB0_106
	v_mov_b32_e32 v1, 0xfc00000
	global_load_dword v2, v1, s[30:31] offset:1024 sc1
	global_load_dword v3, v1, s[30:31] offset:1280 sc1
	global_load_dword v4, v1, s[30:31] offset:1536 sc1
	global_load_dword v5, v1, s[30:31] offset:1792 sc1
	global_load_dword v6, v1, s[30:31] offset:2048 sc1
	global_load_dword v7, v1, s[30:31] offset:2304 sc1
	global_load_dword v8, v1, s[30:31] offset:2560 sc1
	global_load_dword v9, v1, s[30:31] offset:2816 sc1
	s_ashr_i32 s3, s34, 31
	s_lshr_b32 s3, s3, 29
	s_add_i32 s3, s34, s3
	s_ashr_i32 s3, s3, 3
	v_mov_b32_e32 v0, s80
	s_waitcnt vmcnt(0)
	v_cmp_ne_u32_e32 vcc, s3, v2
	s_cbranch_vccnz .LBB0_106
	v_cmp_ne_u32_e32 vcc, s3, v3
	s_cbranch_vccnz .LBB0_106
	v_cmp_ne_u32_e32 vcc, s3, v4
	s_cbranch_vccnz .LBB0_106
	v_cmp_ne_u32_e32 vcc, s3, v5
	s_cbranch_vccnz .LBB0_106
	v_cmp_ne_u32_e32 vcc, s3, v6
	s_cbranch_vccnz .LBB0_106
	v_cmp_ne_u32_e32 vcc, s3, v7
	s_cbranch_vccnz .LBB0_106
	v_cmp_ne_u32_e32 vcc, s3, v8
	s_cbranch_vccnz .LBB0_106
	v_cmp_ne_u32_e32 vcc, s3, v9
	s_cbranch_vccnz .LBB0_106
	s_add_i32 s3, 0, 0x20048
	v_mov_b32_e32 v0, s3
	ds_read_b32 v0, v0
	s_waitcnt lgkmcnt(0)
	v_lshlrev_b32_e32 v0, 3, v0
	v_or_b32_e32 v0, s33, v0
	s_cmp_lg_u32 s34, 0x100
	s_cbranch_scc1 .Lxl_noflag
	v_mov_b32_e32 v1, 0x20050
	ds_write_b32 v1, v1
